# MLA loop: softmax VALU re-spaced by issue cost (exps of the next 4-key half interleaved with the add/cvt of the current one) around the MFMAs
# speedup vs baseline: 1.0066x; 1.0066x over previous
; #define MFMA(a, b, c) __builtin_amdgcn_mfma_f32_32x32x16_bf16((a), (b), (c), 0, 0, 0)
; DI unsigned pk2(float lo, float hi) { f32x2 v = {lo, hi}; b16x2 r = __builtin_convertvector(v, b16x2); return __builtin_bit_cast(unsigned, r); }
; template <int MODE>
; DI void attn_item(const Params& p, int layer, int bh, int qb, char* lds) {
;     ...
;         for (int sub = 0; sub < 2; ++sub) {
; #pragma unroll
;           for (int st = 0; st < QS; ++st) {
;             bf16x8 kf = *(const bf16x8*)(Ks + (32 * sub + l32) * KSTR + ((mp * QS + st) * 16 + hh * 8) * 2);
;             if (st == 0) s[sub] = MFMA(kf, qf[mp][st], c0tile); else s[sub] = MFMA(kf, qf[mp][st], s[sub]);
;           }
;         }
;     ...
;         auto smpass = [&]() {
;           ps = 0.f;
; #pragma unroll
;           for (int sub = 0; sub < 2; ++sub)
; #pragma unroll
;             for (int ks = 0; ks < 2; ++ks)
; #pragma unroll
;               for (int i = 0; i < 4; ++i) {
;                 const float p0 = __builtin_amdgcn_exp2f(s[sub][8 * ks + 2 * i]), p1 = __builtin_amdgcn_exp2f(s[sub][8 * ks + 2 * i + 1]);
;                 ps += p0 + p1; pk[mp][sub][ks][i] = pk2(p0, p1);
;               }
;         };
;         if (first) rebase();
;         smpass();
;         if (!first && __any(!(ps <= PSLIM))) { rebase(); smpass(); }
;         l[mp] += ps;
;         __builtin_amdgcn_sched_barrier(0);
;       }
; #pragma unroll
;       for (int sub = 0; sub < 2; ++sub) {
;         s16x4 vv[8];
;         if (NMAP == 1) {
; #pragma unroll
;           for (int i = 0; i < 8; ++i) vv[i] = vpre[sub * 8 + i];
;         } else {
;           if (sub == 0) trread8<0>(vaddr, vv); else trread8<32 * VSTR>(vaddr, vv);
;         }
;         __builtin_amdgcn_s_setprio(1);
; #pragma unroll
;         for (int ks = 0; ks < 2; ++ks) {
; #pragma unroll
;           for (int dt = 0; dt < 2; ++dt) {
;             s16x4 lo = vv[ks * 4 + dt * 2], hi = vv[ks * 4 + dt * 2 + 1];
;             bf16x8 vf = __builtin_shufflevector(lo, hi, 0, 1, 2, 3, 4, 5, 6, 7);
; #pragma unroll
;             for (int mp = 0; mp < NMAP; ++mp) O[mp][dt] = MFMA(vf, __builtin_bit_cast(bf16x8, pk[mp][sub][ks]), O[mp][dt]);
;           }
;         }
;         __builtin_amdgcn_s_setprio(0);
;         __builtin_amdgcn_sched_barrier(0);
;       }
.Lmla_loop:
	ds_read_b128 v[176:179], v200 offset:27648
	ds_read_b128 v[180:183], v200 offset:27680
	ds_read_b128 v[222:225], v200 offset:27712
	s_waitcnt vmcnt(3)
	ds_write_b128 v202, v[96:99] offset:2048
	ds_write_b64 v203, v[100:101] offset:2048
	ds_write_b128 v207, v[188:191] offset:40960
	buffer_load_dwordx4 v[96:99], v187, s[20:23], s62 offen
	buffer_load_dwordx2 v[100:101], v205, s[20:23], s62 offen
	buffer_load_dwordx4 v[188:191], v187, s[12:15], s29 offen
	s_add_u32 s62, s62, 0x3000
	s_add_u32 s29, s29, 0x2000
	v_exp_f32_e32 v0, v64
	v_exp_f32_e32 v1, v65
	v_exp_f32_e32 v2, v66
	v_exp_f32_e32 v3, v67
	v_exp_f32_e32 v6, v68
	v_add_f32_e32 v10, v0, v1
	s_waitcnt lgkmcnt(5)
	v_mfma_f32_32x32x16_bf16 v[128:143], v[176:179], v[104:107], v[48:63]
	ds_read_b128 v[226:229], v200 offset:27744
	s_waitcnt lgkmcnt(5)
	v_mfma_f32_32x32x16_bf16 v[128:143], v[180:183], v[108:111], v[128:143]
	ds_read_b64_tr_b16 v[176:177], v201 offset:15360
	ds_read_b64_tr_b16 v[178:179], v201 offset:16896
	v_exp_f32_e32 v7, v69
	v_cvt_pk_bf16_f32 v160, v0, v1
	v_exp_f32_e32 v8, v70
	v_add_f32_e32 v10, v10, v2
	v_exp_f32_e32 v9, v71
	s_waitcnt lgkmcnt(6)
	v_mfma_f32_32x32x16_bf16 v[128:143], v[222:225], v[112:115], v[128:143]
	ds_read_b64_tr_b16 v[180:181], v201 offset:15424
	ds_read_b64_tr_b16 v[182:183], v201 offset:16960
	v_add_f32_e32 v10, v10, v3
	v_cvt_pk_bf16_f32 v161, v2, v3
	v_exp_f32_e32 v0, v72
	v_add_f32_e32 v10, v10, v6
	v_exp_f32_e32 v1, v73
	v_add_f32_e32 v10, v10, v7
	s_waitcnt lgkmcnt(4)
	v_mfma_f32_32x32x16_bf16 v[128:143], v[226:229], v[116:119], v[128:143]
	ds_read_b128 v[222:225], v200 offset:27776
	v_exp_f32_e32 v2, v74
	v_cvt_pk_bf16_f32 v162, v6, v7
	v_exp_f32_e32 v3, v75
	v_add_f32_e32 v10, v10, v8
	v_add_f32_e32 v10, v10, v9
	v_cvt_pk_bf16_f32 v163, v8, v9
	s_waitcnt lgkmcnt(3)
	s_nop 0
	v_mfma_f32_32x32x16_bf16 v[32:47], v[176:179], v[160:163], v[32:47]
	ds_read_b128 v[226:229], v200 offset:27808
	v_exp_f32_e32 v6, v76
	v_add_f32_e32 v11, v0, v1
	v_exp_f32_e32 v7, v77
	s_waitcnt lgkmcnt(2)
	v_mfma_f32_32x32x16_bf16 v[16:31], v[180:183], v[160:163], v[16:31]
	ds_read_b128 v[176:179], v200 offset:34304
	v_cvt_pk_bf16_f32 v164, v0, v1
	v_exp_f32_e32 v8, v78
	v_add_f32_e32 v11, v11, v2
	v_exp_f32_e32 v9, v79
	s_waitcnt lgkmcnt(2)
	v_mfma_f32_32x32x16_bf16 v[128:143], v[222:225], v[120:123], v[128:143]
	ds_read_b64_tr_b16 v[180:181], v201 offset:18432
	ds_read_b64_tr_b16 v[182:183], v201 offset:19968
	v_add_f32_e32 v11, v11, v3
	v_cvt_pk_bf16_f32 v165, v2, v3
	v_exp_f32_e32 v0, v80
	v_add_f32_e32 v11, v11, v6
	s_waitcnt lgkmcnt(3)
	v_mfma_f32_32x32x16_bf16 v[128:143], v[226:229], v[124:127], v[128:143]
	ds_read_b64_tr_b16 v[222:223], v201 offset:18496
	ds_read_b64_tr_b16 v[224:225], v201 offset:20032
	v_exp_f32_e32 v1, v81
	v_add_f32_e32 v11, v11, v7
	v_exp_f32_e32 v2, v82
	v_cvt_pk_bf16_f32 v166, v6, v7
	s_waitcnt lgkmcnt(4)
	v_mfma_f32_32x32x16_bf16 v[144:159], v[176:179], v[104:107], v[48:63]
	ds_read_b128 v[226:229], v200 offset:34336
	v_exp_f32_e32 v3, v83
	v_add_f32_e32 v11, v11, v8
	v_add_f32_e32 v11, v11, v9
	v_cvt_pk_bf16_f32 v167, v8, v9
	s_waitcnt lgkmcnt(3)
	s_nop 0
	v_mfma_f32_32x32x16_bf16 v[32:47], v[180:183], v[164:167], v[32:47]
	ds_read_b128 v[176:179], v200 offset:34368
	v_exp_f32_e32 v6, v84
	v_add_f32_e32 v12, v0, v1
	v_exp_f32_e32 v7, v85
	s_waitcnt lgkmcnt(2)
	v_mfma_f32_32x32x16_bf16 v[16:31], v[222:225], v[164:167], v[16:31]
	ds_read_b128 v[180:183], v200 offset:34400
	v_cvt_pk_bf16_f32 v168, v0, v1
	v_exp_f32_e32 v8, v86
	v_add_f32_e32 v12, v12, v2
	v_exp_f32_e32 v9, v87
	s_waitcnt lgkmcnt(2)
	v_mfma_f32_32x32x16_bf16 v[144:159], v[226:229], v[108:111], v[144:159]
	ds_read_b64_tr_b16 v[222:223], v201 offset:21504
	ds_read_b64_tr_b16 v[224:225], v201 offset:23040
	v_add_f32_e32 v12, v12, v3
	v_cvt_pk_bf16_f32 v169, v2, v3
	v_exp_f32_e32 v0, v88
	v_add_f32_e32 v12, v12, v6
	s_waitcnt lgkmcnt(3)
	v_mfma_f32_32x32x16_bf16 v[144:159], v[176:179], v[112:115], v[144:159]
	ds_read_b64_tr_b16 v[226:227], v201 offset:21568
	ds_read_b64_tr_b16 v[228:229], v201 offset:23104
	v_exp_f32_e32 v1, v89
	v_add_f32_e32 v12, v12, v7
	v_exp_f32_e32 v2, v90
	v_cvt_pk_bf16_f32 v170, v6, v7
	s_waitcnt lgkmcnt(4)
	v_mfma_f32_32x32x16_bf16 v[144:159], v[180:183], v[116:119], v[144:159]
	ds_read_b128 v[176:179], v200 offset:34432
	v_exp_f32_e32 v3, v91
	v_add_f32_e32 v12, v12, v8
	v_add_f32_e32 v12, v12, v9
	v_cvt_pk_bf16_f32 v171, v8, v9
	s_waitcnt lgkmcnt(3)
	s_nop 0
	v_mfma_f32_32x32x16_bf16 v[32:47], v[222:225], v[168:171], v[32:47]
	ds_read_b128 v[180:183], v200 offset:34464
	v_exp_f32_e32 v6, v92
	v_add_f32_e32 v13, v0, v1
	v_exp_f32_e32 v7, v93
	s_waitcnt lgkmcnt(2)
	v_mfma_f32_32x32x16_bf16 v[16:31], v[226:229], v[168:171], v[16:31]
	ds_read_b64_tr_b16 v[222:223], v201 offset:24576
	ds_read_b64_tr_b16 v[224:225], v201 offset:26112
	v_cvt_pk_bf16_f32 v172, v0, v1
	v_exp_f32_e32 v8, v94
	v_add_f32_e32 v13, v13, v2
	v_exp_f32_e32 v9, v95
	s_waitcnt lgkmcnt(3)
	v_mfma_f32_32x32x16_bf16 v[144:159], v[176:179], v[120:123], v[144:159]
	ds_read_b64_tr_b16 v[226:227], v201 offset:24640
	ds_read_b64_tr_b16 v[228:229], v201 offset:26176
	v_add_f32_e32 v13, v13, v3
	v_cvt_pk_bf16_f32 v173, v2, v3
	v_add_f32_e32 v13, v13, v6
	v_add_f32_e32 v13, v13, v7
	s_waitcnt lgkmcnt(4)
	v_mfma_f32_32x32x16_bf16 v[144:159], v[180:183], v[124:127], v[144:159]
	v_cvt_pk_bf16_f32 v174, v6, v7
	v_add_f32_e32 v13, v13, v8
	v_add_f32_e32 v13, v13, v9
	v_cvt_pk_bf16_f32 v175, v8, v9
	s_waitcnt lgkmcnt(2)
	s_nop 0
	v_mfma_f32_32x32x16_bf16 v[32:47], v[222:225], v[172:175], v[32:47]
	s_waitcnt lgkmcnt(0)
	v_mfma_f32_32x32x16_bf16 v[16:31], v[226:229], v[172:175], v[16:31]
	v_add_f32_e32 v10, v10, v11
	v_add_f32_e32 v12, v12, v13
	v_add_f32_e32 v10, v10, v12
	v_add_f32_e32 v192, v192, v10
	v_max_f32_e32 v193, v193, v10
	s_waitcnt lgkmcnt(0)
	s_barrier
; #define MFMA(a, b, c) __builtin_amdgcn_mfma_f32_32x32x16_bf16((a), (b), (c), 0, 0, 0)
; DI unsigned pk2(float lo, float hi) { f32x2 v = {lo, hi}; b16x2 r = __builtin_convertvector(v, b16x2); return __builtin_bit_cast(unsigned, r); }
; template <int MODE>
; DI void attn_item(const Params& p, int layer, int bh, int qb, char* lds) {
;     ...
;         for (int sub = 0; sub < 2; ++sub) {
; #pragma unroll
;           for (int st = 0; st < QS; ++st) {
;             bf16x8 kf = *(const bf16x8*)(Ks + (32 * sub + l32) * KSTR + ((mp * QS + st) * 16 + hh * 8) * 2);
;             if (st == 0) s[sub] = MFMA(kf, qf[mp][st], c0tile); else s[sub] = MFMA(kf, qf[mp][st], s[sub]);
;           }
;         }
;     ...
;         auto smpass = [&]() {
;           ps = 0.f;
; #pragma unroll
;           for (int sub = 0; sub < 2; ++sub)
; #pragma unroll
;             for (int ks = 0; ks < 2; ++ks)
; #pragma unroll
;               for (int i = 0; i < 4; ++i) {
;                 const float p0 = __builtin_amdgcn_exp2f(s[sub][8 * ks + 2 * i]), p1 = __builtin_amdgcn_exp2f(s[sub][8 * ks + 2 * i + 1]);
;                 ps += p0 + p1; pk[mp][sub][ks][i] = pk2(p0, p1);
;               }
;         };
;         if (first) rebase();
;         smpass();
;         if (!first && __any(!(ps <= PSLIM))) { rebase(); smpass(); }
;         l[mp] += ps;
;         __builtin_amdgcn_sched_barrier(0);
;       }
; #pragma unroll
;       for (int sub = 0; sub < 2; ++sub) {
;         s16x4 vv[8];
;         if (NMAP == 1) {
; #pragma unroll
;           for (int i = 0; i < 8; ++i) vv[i] = vpre[sub * 8 + i];
;         } else {
;           if (sub == 0) trread8<0>(vaddr, vv); else trread8<32 * VSTR>(vaddr, vv);
;         }
;         __builtin_amdgcn_s_setprio(1);
; #pragma unroll
;         for (int ks = 0; ks < 2; ++ks) {
; #pragma unroll
;           for (int dt = 0; dt < 2; ++dt) {
;             s16x4 lo = vv[ks * 4 + dt * 2], hi = vv[ks * 4 + dt * 2 + 1];
;             bf16x8 vf = __builtin_shufflevector(lo, hi, 0, 1, 2, 3, 4, 5, 6, 7);
; #pragma unroll
;             for (int mp = 0; mp < NMAP; ++mp) O[mp][dt] = MFMA(vf, __builtin_bit_cast(bf16x8, pk[mp][sub][ks]), O[mp][dt]);
;           }
;         }
;         __builtin_amdgcn_s_setprio(0);
;         __builtin_amdgcn_sched_barrier(0);
;       }
	ds_read_b128 v[176:179], v200 offset:2048
	ds_read_b128 v[180:183], v200 offset:2080
	ds_read_b128 v[222:225], v200 offset:2112
	s_waitcnt vmcnt(3)
	ds_write_b128 v202, v[230:233] offset:27648
	ds_write_b64 v203, v[234:235] offset:27648
	ds_write_b128 v207, v[236:239] offset:15360
	buffer_load_dwordx4 v[230:233], v187, s[20:23], s62 offen
	buffer_load_dwordx2 v[234:235], v205, s[20:23], s62 offen
	buffer_load_dwordx4 v[236:239], v187, s[12:15], s29 offen
	s_add_u32 s62, s62, 0x3000
	s_add_u32 s29, s29, 0x2000
	v_exp_f32_e32 v0, v128
	v_exp_f32_e32 v1, v129
	v_exp_f32_e32 v2, v130
	v_exp_f32_e32 v3, v131
	v_exp_f32_e32 v6, v132
	v_add_f32_e32 v10, v0, v1
	s_waitcnt lgkmcnt(5)
	v_mfma_f32_32x32x16_bf16 v[64:79], v[176:179], v[104:107], v[48:63]
	ds_read_b128 v[226:229], v200 offset:2144
	s_waitcnt lgkmcnt(5)
	v_mfma_f32_32x32x16_bf16 v[64:79], v[180:183], v[108:111], v[64:79]
	ds_read_b64_tr_b16 v[176:177], v201 offset:40960
	ds_read_b64_tr_b16 v[178:179], v201 offset:42496
	v_exp_f32_e32 v7, v133
	v_cvt_pk_bf16_f32 v160, v0, v1
	v_exp_f32_e32 v8, v134
	v_add_f32_e32 v10, v10, v2
	v_exp_f32_e32 v9, v135
	s_waitcnt lgkmcnt(6)
	v_mfma_f32_32x32x16_bf16 v[64:79], v[222:225], v[112:115], v[64:79]
	ds_read_b64_tr_b16 v[180:181], v201 offset:41024
	ds_read_b64_tr_b16 v[182:183], v201 offset:42560
	v_add_f32_e32 v10, v10, v3
	v_cvt_pk_bf16_f32 v161, v2, v3
	v_exp_f32_e32 v0, v136
	v_add_f32_e32 v10, v10, v6
	v_exp_f32_e32 v1, v137
	v_add_f32_e32 v10, v10, v7
	s_waitcnt lgkmcnt(4)
	v_mfma_f32_32x32x16_bf16 v[64:79], v[226:229], v[116:119], v[64:79]
	ds_read_b128 v[222:225], v200 offset:2176
	v_exp_f32_e32 v2, v138
	v_cvt_pk_bf16_f32 v162, v6, v7
	v_exp_f32_e32 v3, v139
	v_add_f32_e32 v10, v10, v8
	v_add_f32_e32 v10, v10, v9
	v_cvt_pk_bf16_f32 v163, v8, v9
	s_waitcnt lgkmcnt(3)
	s_nop 0
	v_mfma_f32_32x32x16_bf16 v[32:47], v[176:179], v[160:163], v[32:47]
	ds_read_b128 v[226:229], v200 offset:2208
	v_exp_f32_e32 v6, v140
	v_add_f32_e32 v11, v0, v1
	v_exp_f32_e32 v7, v141
	s_waitcnt lgkmcnt(2)
	v_mfma_f32_32x32x16_bf16 v[16:31], v[180:183], v[160:163], v[16:31]
	ds_read_b128 v[176:179], v200 offset:8704
	v_cvt_pk_bf16_f32 v164, v0, v1
	v_exp_f32_e32 v8, v142
	v_add_f32_e32 v11, v11, v2
	v_exp_f32_e32 v9, v143
	s_waitcnt lgkmcnt(2)
	v_mfma_f32_32x32x16_bf16 v[64:79], v[222:225], v[120:123], v[64:79]
	ds_read_b64_tr_b16 v[180:181], v201 offset:44032
	ds_read_b64_tr_b16 v[182:183], v201 offset:45568
	v_add_f32_e32 v11, v11, v3
	v_cvt_pk_bf16_f32 v165, v2, v3
	v_exp_f32_e32 v0, v144
	v_add_f32_e32 v11, v11, v6
	s_waitcnt lgkmcnt(3)
	v_mfma_f32_32x32x16_bf16 v[64:79], v[226:229], v[124:127], v[64:79]
	ds_read_b64_tr_b16 v[222:223], v201 offset:44096
	ds_read_b64_tr_b16 v[224:225], v201 offset:45632
	v_exp_f32_e32 v1, v145
	v_add_f32_e32 v11, v11, v7
	v_exp_f32_e32 v2, v146
	v_cvt_pk_bf16_f32 v166, v6, v7
	s_waitcnt lgkmcnt(4)
	v_mfma_f32_32x32x16_bf16 v[80:95], v[176:179], v[104:107], v[48:63]
	ds_read_b128 v[226:229], v200 offset:8736
	v_exp_f32_e32 v3, v147
	v_add_f32_e32 v11, v11, v8
	v_add_f32_e32 v11, v11, v9
	v_cvt_pk_bf16_f32 v167, v8, v9
	s_waitcnt lgkmcnt(3)
	s_nop 0
	v_mfma_f32_32x32x16_bf16 v[32:47], v[180:183], v[164:167], v[32:47]
	ds_read_b128 v[176:179], v200 offset:8768
	v_exp_f32_e32 v6, v148
	v_add_f32_e32 v12, v0, v1
	v_exp_f32_e32 v7, v149
	s_waitcnt lgkmcnt(2)
	v_mfma_f32_32x32x16_bf16 v[16:31], v[222:225], v[164:167], v[16:31]
	ds_read_b128 v[180:183], v200 offset:8800
	v_cvt_pk_bf16_f32 v168, v0, v1
	v_exp_f32_e32 v8, v150
	v_add_f32_e32 v12, v12, v2
	v_exp_f32_e32 v9, v151
	s_waitcnt lgkmcnt(2)
	v_mfma_f32_32x32x16_bf16 v[80:95], v[226:229], v[108:111], v[80:95]
	ds_read_b64_tr_b16 v[222:223], v201 offset:47104
	ds_read_b64_tr_b16 v[224:225], v201 offset:48640
	v_add_f32_e32 v12, v12, v3
	v_cvt_pk_bf16_f32 v169, v2, v3
	v_exp_f32_e32 v0, v152
	v_add_f32_e32 v12, v12, v6
	s_waitcnt lgkmcnt(3)
	v_mfma_f32_32x32x16_bf16 v[80:95], v[176:179], v[112:115], v[80:95]
	ds_read_b64_tr_b16 v[226:227], v201 offset:47168
	ds_read_b64_tr_b16 v[228:229], v201 offset:48704
	v_exp_f32_e32 v1, v153
	v_add_f32_e32 v12, v12, v7
	v_exp_f32_e32 v2, v154
	v_cvt_pk_bf16_f32 v170, v6, v7
	s_waitcnt lgkmcnt(4)
	v_mfma_f32_32x32x16_bf16 v[80:95], v[180:183], v[116:119], v[80:95]
	ds_read_b128 v[176:179], v200 offset:8832
	v_exp_f32_e32 v3, v155
	v_add_f32_e32 v12, v12, v8
	v_add_f32_e32 v12, v12, v9
	v_cvt_pk_bf16_f32 v171, v8, v9
	s_waitcnt lgkmcnt(3)
	s_nop 0
	v_mfma_f32_32x32x16_bf16 v[32:47], v[222:225], v[168:171], v[32:47]
	ds_read_b128 v[180:183], v200 offset:8864
	v_exp_f32_e32 v6, v156
	v_add_f32_e32 v13, v0, v1
	v_exp_f32_e32 v7, v157
	s_waitcnt lgkmcnt(2)
	v_mfma_f32_32x32x16_bf16 v[16:31], v[226:229], v[168:171], v[16:31]
	ds_read_b64_tr_b16 v[222:223], v201 offset:50176
	ds_read_b64_tr_b16 v[224:225], v201 offset:51712
	v_cvt_pk_bf16_f32 v172, v0, v1
	v_exp_f32_e32 v8, v158
	v_add_f32_e32 v13, v13, v2
	v_exp_f32_e32 v9, v159
	s_waitcnt lgkmcnt(3)
	v_mfma_f32_32x32x16_bf16 v[80:95], v[176:179], v[120:123], v[80:95]
	ds_read_b64_tr_b16 v[226:227], v201 offset:50240
	ds_read_b64_tr_b16 v[228:229], v201 offset:51776
	v_add_f32_e32 v13, v13, v3
	v_cvt_pk_bf16_f32 v173, v2, v3
	v_add_f32_e32 v13, v13, v6
	v_add_f32_e32 v13, v13, v7
	s_waitcnt lgkmcnt(4)
	v_mfma_f32_32x32x16_bf16 v[80:95], v[180:183], v[124:127], v[80:95]
	v_cvt_pk_bf16_f32 v174, v6, v7
	v_add_f32_e32 v13, v13, v8
	v_add_f32_e32 v13, v13, v9
	v_cvt_pk_bf16_f32 v175, v8, v9
	s_waitcnt lgkmcnt(2)
	s_nop 0
	v_mfma_f32_32x32x16_bf16 v[32:47], v[222:225], v[172:175], v[32:47]
	s_waitcnt lgkmcnt(0)
	v_mfma_f32_32x32x16_bf16 v[16:31], v[226:229], v[172:175], v[16:31]
	v_add_f32_e32 v10, v10, v11
	v_add_f32_e32 v12, v12, v13
	v_add_f32_e32 v10, v10, v12
	v_add_f32_e32 v192, v192, v10
	v_max_f32_e32 v193, v193, v10
	s_add_u32 s28, s28, 2
	s_cmpk_lt_u32 s28, 0x80
	s_waitcnt lgkmcnt(0)
	s_barrier
; DI unsigned pk2(float lo, float hi) { f32x2 v = {lo, hi}; b16x2 r = __builtin_convertvector(v, b16x2); return __builtin_bit_cast(unsigned, r); }
; DI float bflo(unsigned w) { return __uint_as_float(w << 16); }
; DI float bfhi(unsigned w) { return __uint_as_float(w & 0xffff0000u); }
; template <int MODE>
; DI void attn_item(const Params& p, int layer, int bh, int qb, char* lds) {
;     ...
;         if (!first && __any(!(ps <= PSLIM))) { rebase(); smpass(); }
;         l[mp] += ps;
;     ...
;   __syncthreads();
;   const size_t trow = (size_t)b * S + q0w + l32;
;   const u16* grow = (const u16*)(p.ws + OFF_H) + trow * DIN + C_GATE + ocol;
;   u16* orow = (u16*)(p.ws + OFF_OB) + trow * DM + ocol;
;   float inv0 = 1.f / xchg_sum(l[0]);
;   if (MODE == 1) {
;     const float* lm = (const float*)(p.ws + OFF_LAM);
;     const float lam = lm[layer], post = lm[4 + layer];
;     const float inv1 = lam / xchg_sum(l[1]);
;     float ss = 0.f;
; #pragma unroll
;     for (int dt = 0; dt < 2; ++dt)
; #pragma unroll
;       for (int r = 0; r < 16; ++r) { float v = O[0][dt][r] * inv0 - O[NMAP - 1][dt][r] * inv1; O[0][dt][r] = v; ss += v * v; }
;     ss = xchg_sum(ss);
;     inv0 = rsqrtf(ss * (1.f / 64.f) + 1e-6f) * post;
;   }
; #pragma unroll
;   for (int dt = 0; dt < 2; ++dt)
; #pragma unroll
;     for (int g = 0; g < 4; ++g) {
;       const int d = 32 * dt + 8 * g + 4 * hh;
;       u32x2 gw = *(const u32x2*)(grow + d);
;       float v0 = O[0][dt][4 * g + 0] * inv0, v1 = O[0][dt][4 * g + 1] * inv0, v2 = O[0][dt][4 * g + 2] * inv0, v3 = O[0][dt][4 * g + 3] * inv0;
;       if (MODE == 1) { const float* sl = p.subln + layer * 64 + d; v0 *= sl[0]; v1 *= sl[1]; v2 *= sl[2]; v3 *= sl[3]; }
;       v0 *= bflo(gw[0]); v1 *= bfhi(gw[0]); v2 *= bflo(gw[1]); v3 *= bfhi(gw[1]);
;       u32x2 ow = {pk2(v0, v1), pk2(v2, v3)};
;     ...
;       if (MODE == PROBE_ZERO_MODE) { ow[0] = 0u; ow[1] = 0u; }
;     ...
;       *(u32x2*)(orow + d) = ow;
	s_cbranch_scc1 .Lmla_loop
	s_waitcnt vmcnt(0)
	s_lshl_b64 s[6:7], s[10:11], 13
	v_ashrrev_i32_e32 v187, 31, v186
	v_lshl_add_u64 v[0:1], s[6:7], 0, v[186:187]
	v_or_b32_e32 v0, v0, v204
	v_mov_b32_e32 v2, s34
	v_mov_b32_e32 v3, s35
	v_mad_u64_u32 v[2:3], s[6:7], v0, s64, v[2:3]
	v_mad_i32_i24 v3, v1, s64, v3
	s_lshl_b32 s4, s52, 7
	v_lshl_add_u32 v12, v206, 1, s4
	v_mov_b32_e32 v13, 0
	v_lshl_add_u64 v[6:7], v[2:3], 0, v[12:13]
	s_mov_b64 s[6:7], 0x6058ec0
	v_lshl_add_u64 v[6:7], v[6:7], 0, s[6:7]
	global_load_dwordx2 v[64:65], v[6:7], off offset:0
	global_load_dwordx2 v[66:67], v[6:7], off offset:16
	global_load_dwordx2 v[68:69], v[6:7], off offset:32
	global_load_dwordx2 v[70:71], v[6:7], off offset:48
	global_load_dwordx2 v[72:73], v[6:7], off offset:64
	global_load_dwordx2 v[74:75], v[6:7], off offset:80
	global_load_dwordx2 v[76:77], v[6:7], off offset:96
	global_load_dwordx2 v[78:79], v[6:7], off offset:112
	v_readlane_b32 s6, v254, 49
	v_readlane_b32 s7, v254, 50
	v_lshlrev_b64 v[0:1], 11, v[0:1]
	s_nop 0
	v_lshl_add_u64 v[0:1], s[6:7], 0, v[0:1]
	v_lshl_add_u64 v[8:9], v[0:1], 0, v[12:13]
	v_cmp_nge_f32_e32 vcc, s94, v193
	s_nop 0
	s_cmp_lg_u64 vcc, 0
	s_cselect_b32 s24, 1, 0
	v_mov_b32_e32 v196, s24
	v_lshrrev_b32_e32 v197, 6, v184
	v_lshlrev_b32_e32 v197, 2, v197
	ds_write_b32 v197, v196 offset:0
	s_waitcnt lgkmcnt(0)
	s_barrier
	v_mov_b32_e32 v197, 0
	ds_read_b128 v[176:179], v197 offset:0
	ds_read_b128 v[180:183], v197 offset:16
	v_mov_b32_e32 v2, v192
	s_nop 1
	v_permlane32_swap_b32_e32 v192, v2
	v_add_f32_e32 v2, v192, v2
	v_div_scale_f32 v3, s[4:5], v2, v2, 1.0
	v_rcp_f32_e32 v4, v3
	s_nop 0
	v_fma_f32 v10, -v3, v4, 1.0
	v_fmac_f32_e32 v4, v10, v4
	v_div_scale_f32 v10, vcc, 1.0, v2, 1.0
	v_mul_f32_e32 v11, v10, v4
	v_fma_f32 v12, -v3, v11, v10
	v_fmac_f32_e32 v11, v12, v4
	v_fma_f32 v3, -v3, v11, v10
	s_nop 1
	v_div_fmas_f32 v3, v3, v4, v11
	v_div_fixup_f32 v2, v3, v2, 1.0
	s_waitcnt lgkmcnt(0)
	v_or3_b32 v196, v176, v177, v178
	v_or3_b32 v196, v196, v179, v180
	v_or3_b32 v196, v196, v181, v182
	v_or_b32_e32 v196, v196, v183
	s_nop 0
	v_readfirstlane_b32 s24, v196
	s_barrier
	s_cmp_lg_u32 s24, 0
	s_cbranch_scc1 .Lmla_slow
	s_waitcnt vmcnt(0)
	v_mul_f32_e32 v32, v32, v2
	v_mul_f32_e32 v33, v33, v2
	v_mul_f32_e32 v34, v34, v2
	v_mul_f32_e32 v35, v35, v2
	v_lshlrev_b32_e32 v196, 16, v64
	v_and_b32_e32 v197, 0xffff0000, v64
	v_mul_f32_e32 v32, v32, v196
	v_mul_f32_e32 v33, v33, v197
	v_lshlrev_b32_e32 v196, 16, v65
	v_and_b32_e32 v197, 0xffff0000, v65
	v_mul_f32_e32 v34, v34, v196
	v_mul_f32_e32 v35, v35, v197
	v_cvt_pk_bf16_f32 v32, v32, v33
	v_cvt_pk_bf16_f32 v33, v34, v35
	global_store_dwordx2 v[8:9], v[32:33], off offset:0
	v_mul_f32_e32 v36, v36, v2
	v_mul_f32_e32 v37, v37, v2
	v_mul_f32_e32 v38, v38, v2
	v_mul_f32_e32 v39, v39, v2
	v_lshlrev_b32_e32 v196, 16, v66
	v_and_b32_e32 v197, 0xffff0000, v66
	v_mul_f32_e32 v36, v36, v196
	v_mul_f32_e32 v37, v37, v197
	v_lshlrev_b32_e32 v196, 16, v67
	v_and_b32_e32 v197, 0xffff0000, v67
	v_mul_f32_e32 v38, v38, v196
	v_mul_f32_e32 v39, v39, v197
	v_cvt_pk_bf16_f32 v36, v36, v37
	v_cvt_pk_bf16_f32 v37, v38, v39
	global_store_dwordx2 v[8:9], v[36:37], off offset:16
	v_mul_f32_e32 v40, v40, v2
	v_mul_f32_e32 v41, v41, v2
	v_mul_f32_e32 v42, v42, v2
	v_mul_f32_e32 v43, v43, v2
	v_lshlrev_b32_e32 v196, 16, v68
	v_and_b32_e32 v197, 0xffff0000, v68
	v_mul_f32_e32 v40, v40, v196
	v_mul_f32_e32 v41, v41, v197
	v_lshlrev_b32_e32 v196, 16, v69
	v_and_b32_e32 v197, 0xffff0000, v69
	v_mul_f32_e32 v42, v42, v196
	v_mul_f32_e32 v43, v43, v197
	v_cvt_pk_bf16_f32 v40, v40, v41
	v_cvt_pk_bf16_f32 v41, v42, v43
	global_store_dwordx2 v[8:9], v[40:41], off offset:32
	v_mul_f32_e32 v44, v44, v2
	v_mul_f32_e32 v45, v45, v2
	v_mul_f32_e32 v46, v46, v2
	v_mul_f32_e32 v47, v47, v2
	v_lshlrev_b32_e32 v196, 16, v70
	v_and_b32_e32 v197, 0xffff0000, v70
	v_mul_f32_e32 v44, v44, v196
	v_mul_f32_e32 v45, v45, v197
	v_lshlrev_b32_e32 v196, 16, v71
	v_and_b32_e32 v197, 0xffff0000, v71
	v_mul_f32_e32 v46, v46, v196
	v_mul_f32_e32 v47, v47, v197
	v_cvt_pk_bf16_f32 v44, v44, v45
	v_cvt_pk_bf16_f32 v45, v46, v47
	global_store_dwordx2 v[8:9], v[44:45], off offset:48
	v_mul_f32_e32 v16, v16, v2
	v_mul_f32_e32 v17, v17, v2
	v_mul_f32_e32 v18, v18, v2
	v_mul_f32_e32 v19, v19, v2
	v_lshlrev_b32_e32 v196, 16, v72
	v_and_b32_e32 v197, 0xffff0000, v72
	v_mul_f32_e32 v16, v16, v196
	v_mul_f32_e32 v17, v17, v197
	v_lshlrev_b32_e32 v196, 16, v73
	v_and_b32_e32 v197, 0xffff0000, v73
	v_mul_f32_e32 v18, v18, v196
	v_mul_f32_e32 v19, v19, v197
	v_cvt_pk_bf16_f32 v16, v16, v17
	v_cvt_pk_bf16_f32 v17, v18, v19
	global_store_dwordx2 v[8:9], v[16:17], off offset:64
	v_mul_f32_e32 v20, v20, v2
	v_mul_f32_e32 v21, v21, v2
	v_mul_f32_e32 v22, v22, v2
	v_mul_f32_e32 v23, v23, v2
	v_lshlrev_b32_e32 v196, 16, v74
	v_and_b32_e32 v197, 0xffff0000, v74
	v_mul_f32_e32 v20, v20, v196
	v_mul_f32_e32 v21, v21, v197
	v_lshlrev_b32_e32 v196, 16, v75
	v_and_b32_e32 v197, 0xffff0000, v75
	v_mul_f32_e32 v22, v22, v196
	v_mul_f32_e32 v23, v23, v197
	v_cvt_pk_bf16_f32 v20, v20, v21
	v_cvt_pk_bf16_f32 v21, v22, v23
	global_store_dwordx2 v[8:9], v[20:21], off offset:80
	v_mul_f32_e32 v24, v24, v2
	v_mul_f32_e32 v25, v25, v2
	v_mul_f32_e32 v26, v26, v2
	v_mul_f32_e32 v27, v27, v2
	v_lshlrev_b32_e32 v196, 16, v76
	v_and_b32_e32 v197, 0xffff0000, v76
	v_mul_f32_e32 v24, v24, v196
	v_mul_f32_e32 v25, v25, v197
	v_lshlrev_b32_e32 v196, 16, v77
	v_and_b32_e32 v197, 0xffff0000, v77
	v_mul_f32_e32 v26, v26, v196
	v_mul_f32_e32 v27, v27, v197
	v_cvt_pk_bf16_f32 v24, v24, v25
	v_cvt_pk_bf16_f32 v25, v26, v27
	global_store_dwordx2 v[8:9], v[24:25], off offset:96
	v_mul_f32_e32 v28, v28, v2
	v_mul_f32_e32 v29, v29, v2
	v_mul_f32_e32 v30, v30, v2
	v_mul_f32_e32 v31, v31, v2
	v_lshlrev_b32_e32 v196, 16, v78
	v_and_b32_e32 v197, 0xffff0000, v78
	v_mul_f32_e32 v28, v28, v196
	v_mul_f32_e32 v29, v29, v197
	v_lshlrev_b32_e32 v196, 16, v79
	v_and_b32_e32 v197, 0xffff0000, v79
	v_mul_f32_e32 v30, v30, v196
	v_mul_f32_e32 v31, v31, v197
	v_cvt_pk_bf16_f32 v28, v28, v29
	v_cvt_pk_bf16_f32 v29, v30, v31
	global_store_dwordx2 v[8:9], v[28:29], off offset:112
	s_branch .LBB0_321
